# phaseA pass order rotated: owner runs the gate passes unclaimed, helpers get the cheap-epilogue passes
# speedup vs baseline: 1.0097x; 1.0093x over previous
; DI const bf16_t* wp(const Params& p, int l, size_t off) { return (const bf16_t*)(p.ws + OFF_WP) + (size_t)l * PW_LAYER + off; }
; template <int MT> DI void phaseB(const Params& p, int l, int t, unsigned char* lds) {
;     ...
;     EpiUp<MT> eu; eu.priv = priv; eu.d2 = d2;
;     eu.halo = (float*)(ws + OFF_UHALO) + (size_t)t * 2 * DFF2;
;     eu.pconv = t == NTILE - 1 ? p.out + O_PCONV + (size_t)l * 2 * DFF2 : nullptr;
;     eu.sconv = p.out + O_SCONV + ((size_t)l * 8 + 2 * t) * 2 * DFF2;
;     gemm64<1024, MT>(xb, DM, d2, wp(p, l, PW_UP), DFF2 / UW, lds, eu);
.LBB0_705:
	v_readlane_b32 s0, v254, 57
	s_nop 3
	s_cmp_lt_u32 s0, 4
	s_cbranch_scc1 .Lhu_done
	s_cmp_lt_u32 s0, 4
	s_cbranch_scc1 .Lhu_sel
	s_and_b32 s0, s0, 31
	s_cmp_gt_u32 s0, 4
	s_cbranch_scc1 .Lhu_done

;     ...
;     for (int pass = 0; pass * NWAVE < NU; ++pass) {
;         const int unit = pass * NWAVE + wave;
;         const bool active = unit < NU;
;         const int ucl = active ? unit : NU - 1;
.Lm3a_go:
	s_add_u32 s6, s88, 4
	s_cmp_ge_u32 s6, 9
	s_cselect_b32 s7, 9, 0
	s_sub_u32 s6, s6, s7
	s_lshl_b32 s2, s6, 3
	v_add_u32_e32 v232, s2, v223

;     ...
;     for (int pass = 0; pass * NWAVE < NU; ++pass) {
;         const int unit = pass * NWAVE + wave;
;         const bool active = unit < NU;
;         const int ucl = active ? unit : NU - 1;
.Lha_c_w:
	s_barrier
	ds_read_b32 v3, v2
	s_waitcnt lgkmcnt(0)
	v_readfirstlane_b32 s88, v3
	s_nop 3
	s_add_u32 s88, s88, 4
	s_cmp_ge_u32 s88, 9
	s_cbranch_scc1 .Lha_next
	s_add_u32 s6, s88, 4
	s_cmp_ge_u32 s6, 9
	s_cselect_b32 s7, 9, 0
	s_sub_u32 s6, s6, s7
	s_lshl_b32 s2, s6, 3
	v_add_u32_e32 v232, s2, v223
